# norm_prepass of the three pre-norm GEMM phases: ss-partial loads for all of a workgroup's tiles issued up front (one memory round trip instead of eight); NA bias loads de-serialized; no precision chan
# speedup vs baseline: 1.0020x; 1.0020x over previous
; DI int get_tid() { int t = threadIdx.x; asm volatile("" : "+v"(t)); return t; }
; #define LAS __attribute__((address_space(3)))
; #define PH_BEGIN(n) if (ph_lo <= (n) && (n) < ph_hi) { LAUNDER(q); char* ws = q.ws; (void)ws;
; DI void norm_prepass(const float* __restrict__ ss, const pg8::StaticOrder& S, LAS float* tab) {
;   const int tid = get_tid();
;   const int row = tid >> 1, half = tid & 1;
;   pg8::Unit u;
;   for (int i = 0; i < 8 && S.next(i, u); ++i) {
;     const f32x4* sp = (const f32x4*)(ss + (size_t)(u.pm * 256 + row) * 16 + half * 8);
;     const f32x4 a = sp[0], b = sp[1];
;     float t = a[0]; t += a[1]; t += a[2]; t += a[3]; t += b[0]; t += b[1]; t += b[2]; t += b[3];
;     const float o = shx(t, 1, tid & 63);
;     const float tot = half ? (o + t) : (t + o);
;     if (!half) tab[i * 256 + row] = rsqrtf(tot * (1.f / 1024.f) + EPS);
;   }
; __global__ void __launch_bounds__(512) mega(Params p, int ph_lo, int ph_hi) {
;     ...
;   for (int L = 0; L < 4; ++L) {
;     const int pb = 1 + 8 * L, li = L >> 1;
;     const bool even = (L & 1) == 0;
;     if (even) {
;       PH_BEGIN(pb + 1)
.LBB0_335:
	s_lshr_b32 s2, s51, 1
	v_writelane_b32 v237, s2, 4
	s_lshl_b32 s4, s51, 3
	v_readlane_b32 s10, v241, 29
	v_writelane_b32 v237, s3, 5
	s_and_b32 s2, s51, 1
	s_cmp_eq_u32 s2, 0
	s_cselect_b64 s[6:7], -1, 0
	v_writelane_b32 v237, s6, 6
	s_cmp_eq_u32 s2, 1
	s_cselect_b64 s[2:3], -1, 0
	v_writelane_b32 v237, s7, 7
	s_or_b32 s6, s4, 2
	v_readlane_b32 s11, v241, 30
	s_cmp_le_i32 s10, s6
	v_writelane_b32 v237, s4, 8
	s_cselect_b64 s[4:5], -1, 0
	s_cmp_lt_i32 s6, s11
	s_cselect_b64 s[6:7], -1, 0
	s_and_b64 vcc, exec, s[2:3]
	s_mov_b64 s[2:3], 0
	v_writelane_b32 v237, s2, 9
	s_and_b64 s[6:7], s[4:5], s[6:7]
	s_mov_b64 s[4:5], -1
	v_writelane_b32 v237, s3, 10
	v_writelane_b32 v237, s51, 11
	s_cbranch_vccz .LBB0_652
	s_andn2_b64 vcc, exec, s[6:7]
	s_cbranch_vccnz .LBB0_556
	s_mov_b64 s[2:3], 0
	v_readlane_b32 s4, v241, 1
	v_readlane_b32 s5, v241, 2
	s_add_u32 s10, s4, s2
	s_addc_u32 s11, s5, s3
	v_readlane_b32 s4, v241, 47
	v_readlane_b32 s5, v241, 48
	v_mov_b32_e32 v3, v182
	v_cmp_ne_u32_e64 s[2:3], 1, v183
	s_andn2_b64 vcc, exec, s[4:5]
	s_cbranch_vccnz .LBB0_362
	v_and_b32_e32 v14, 1, v3
	v_lshlrev_b32_e32 v144, 5, v14
	s_waitcnt lgkmcnt(0)
	v_lshl_add_u64 v[0:1], s[10:11], 0, v[144:145]
	s_mov_b64 s[4:5], 0x5fa4100
	v_ashrrev_i32_e32 v2, 1, v3
	v_lshl_add_u64 v[0:1], v[0:1], 0, s[4:5]
	v_readlane_b32 s4, v241, 49
	v_lshlrev_b32_e32 v3, 2, v3
	s_nop 0
	v_add_u32_e32 v4, s4, v2
	v_ashrrev_i32_e32 v5, 31, v4
	v_lshlrev_b64 v[4:5], 6, v[4:5]
	v_lshl_add_u64 v[4:5], v[0:1], 0, v[4:5]
	global_load_dwordx4 v[6:9], v[4:5], off
	global_load_dwordx4 v[10:13], v[4:5], off offset:16
	v_readlane_b32 s12, v239, 42
	v_readlane_b32 s13, v239, 43
	s_andn2_b64 vcc, exec, s[12:13]
	s_cbranch_vccnz .Lnpa_done
	v_readlane_b32 s9, v240, 57
	s_nop 0
	s_nop 0
	v_add_u32_e32 v90, s9, v2
	v_ashrrev_i32_e32 v91, 31, v90
	v_lshlrev_b64 v[90:91], 6, v[90:91]
	v_lshl_add_u64 v[92:93], v[0:1], 0, v[90:91]
	global_load_dwordx4 v[34:37], v[92:93], off
	s_nop 0
	global_load_dwordx4 v[38:41], v[92:93], off offset:16
	v_readlane_b32 s12, v239, 46
	v_readlane_b32 s13, v239, 47
	s_andn2_b64 vcc, exec, s[12:13]
	s_cbranch_vccnz .Lnpa_done
	v_readlane_b32 s9, v240, 58
	s_nop 0
	s_nop 0
	v_add_u32_e32 v90, s9, v2
	v_ashrrev_i32_e32 v91, 31, v90
	v_lshlrev_b64 v[90:91], 6, v[90:91]
	v_lshl_add_u64 v[92:93], v[0:1], 0, v[90:91]
	global_load_dwordx4 v[42:45], v[92:93], off
	s_nop 0
	global_load_dwordx4 v[46:49], v[92:93], off offset:16
	v_readlane_b32 s12, v239, 57
	v_readlane_b32 s13, v239, 58
	s_andn2_b64 vcc, exec, s[12:13]
	s_cbranch_vccnz .Lnpa_done
	v_readlane_b32 s9, v240, 59
	s_nop 0
	s_nop 0
	v_add_u32_e32 v90, s9, v2
	v_ashrrev_i32_e32 v91, 31, v90
	v_lshlrev_b64 v[90:91], 6, v[90:91]
	v_lshl_add_u64 v[92:93], v[0:1], 0, v[90:91]
	global_load_dwordx4 v[50:53], v[92:93], off
	s_nop 0
	global_load_dwordx4 v[54:57], v[92:93], off offset:16
	v_readlane_b32 s12, v238, 3
	v_readlane_b32 s13, v238, 4
	s_andn2_b64 vcc, exec, s[12:13]
	s_cbranch_vccnz .Lnpa_done
	v_readlane_b32 s9, v240, 60
	s_nop 0
	s_nop 0
	v_add_u32_e32 v90, s9, v2
	v_ashrrev_i32_e32 v91, 31, v90
	v_lshlrev_b64 v[90:91], 6, v[90:91]
	v_lshl_add_u64 v[92:93], v[0:1], 0, v[90:91]
	global_load_dwordx4 v[58:61], v[92:93], off
	s_nop 0
	global_load_dwordx4 v[62:65], v[92:93], off offset:16
	v_readlane_b32 s12, v238, 9
	v_readlane_b32 s13, v238, 10
	s_andn2_b64 vcc, exec, s[12:13]
	s_cbranch_vccnz .Lnpa_done
	v_readlane_b32 s9, v240, 61
	s_nop 0
	s_nop 0
	v_add_u32_e32 v90, s9, v2
	v_ashrrev_i32_e32 v91, 31, v90
	v_lshlrev_b64 v[90:91], 6, v[90:91]
	v_lshl_add_u64 v[92:93], v[0:1], 0, v[90:91]
	global_load_dwordx4 v[66:69], v[92:93], off
	s_nop 0
	global_load_dwordx4 v[70:73], v[92:93], off offset:16
	v_readlane_b32 s12, v238, 15
	v_readlane_b32 s13, v238, 16
	s_andn2_b64 vcc, exec, s[12:13]
	s_cbranch_vccnz .Lnpa_done
	v_readlane_b32 s9, v240, 62
	s_nop 0
	s_nop 0
	v_add_u32_e32 v90, s9, v2
	v_ashrrev_i32_e32 v91, 31, v90
	v_lshlrev_b64 v[90:91], 6, v[90:91]
	v_lshl_add_u64 v[92:93], v[0:1], 0, v[90:91]
	global_load_dwordx4 v[74:77], v[92:93], off
	s_nop 0
	global_load_dwordx4 v[78:81], v[92:93], off offset:16
	v_readlane_b32 s12, v238, 21
	v_readlane_b32 s13, v238, 22
	s_andn2_b64 vcc, exec, s[12:13]
	s_cbranch_vccnz .Lnpa_done
	v_readlane_b32 s9, v240, 63
	s_nop 0
	s_nop 0
	v_add_u32_e32 v90, s9, v2
	v_ashrrev_i32_e32 v91, 31, v90
	v_lshlrev_b64 v[90:91], 6, v[90:91]
	v_lshl_add_u64 v[92:93], v[0:1], 0, v[90:91]
	global_load_dwordx4 v[82:85], v[92:93], off
	global_load_dwordx4 v[86:89], v[92:93], off offset:16
.Lnpa_done:
	v_bitop3_b32 v4, v3, 4, v190 bitop3:0x6c
	v_readlane_b32 s4, v238, 44
	s_waitcnt vmcnt(0)
	v_add_f32_e32 v3, v6, v7
	v_add_f32_e32 v3, v8, v3
	v_add_f32_e32 v3, v9, v3
	s_waitcnt vmcnt(0)
	v_add_f32_e32 v3, v10, v3
	v_add_f32_e32 v3, v11, v3
	v_add_f32_e32 v3, v12, v3
	v_add_f32_e32 v5, v13, v3
	ds_bpermute_b32 v6, v4, v5
	v_lshl_add_u32 v3, v2, 2, s4
	v_cmp_eq_u32_e64 s[4:5], 0, v14
	s_and_saveexec_b64 s[12:13], s[4:5]
	s_cbranch_execz .LBB0_340
	s_waitcnt lgkmcnt(0)
	v_add_f32_e32 v5, v5, v6
	v_fmamk_f32 v5, v5, 0x3a800000, v184
	s_mov_b32 s9, 0x800000
	v_mul_f32_e32 v6, 0x4b800000, v5
	v_cmp_gt_f32_e32 vcc, s9, v5
	s_nop 1
	v_cndmask_b32_e32 v5, v5, v6, vcc
	v_rsq_f32_e32 v5, v5
	s_nop 0
	v_mul_f32_e32 v6, 0x45800000, v5
	v_cndmask_b32_e32 v5, v5, v6, vcc
	ds_write_b32 v3, v5
; DI void norm_prepass(const float* __restrict__ ss, const pg8::StaticOrder& S, LAS float* tab) {
;     ...
;   for (int i = 0; i < 8 && S.next(i, u); ++i) {
;     const f32x4* sp = (const f32x4*)(ss + (size_t)(u.pm * 256 + row) * 16 + half * 8);
;     const f32x4 a = sp[0], b = sp[1];
;     float t = a[0]; t += a[1]; t += a[2]; t += a[3]; t += b[0]; t += b[1]; t += b[2]; t += b[3];
;     const float o = shx(t, 1, tid & 63);
;     const float tot = half ? (o + t) : (t + o);
;     if (!half) tab[i * 256 + row] = rsqrtf(tot * (1.f / 1024.f) + EPS);
;   }
.LBB0_340:
	s_or_b64 exec, exec, s[12:13]
	v_readlane_b32 s12, v239, 42
	v_readlane_b32 s13, v239, 43
	s_andn2_b64 vcc, exec, s[12:13]
	s_cbranch_vccnz .LBB0_362
	v_readlane_b32 s9, v240, 57
	s_waitcnt lgkmcnt(0)
	s_nop 0
	v_add_u32_e32 v6, s9, v2
	v_ashrrev_i32_e32 v7, 31, v6
	v_lshlrev_b64 v[6:7], 6, v[6:7]
	v_lshl_add_u64 v[10:11], v[0:1], 0, v[6:7]
	s_nop 0
	s_waitcnt vmcnt(1)
	v_add_f32_e32 v5, v34, v35
	v_add_f32_e32 v5, v36, v5
	v_add_f32_e32 v5, v37, v5
	s_waitcnt vmcnt(0)
	v_add_f32_e32 v5, v38, v5
	v_add_f32_e32 v5, v39, v5
	v_add_f32_e32 v5, v40, v5
	v_add_f32_e32 v5, v41, v5
	ds_bpermute_b32 v6, v4, v5
	s_and_saveexec_b64 s[12:13], s[4:5]
	s_cbranch_execz .LBB0_343
	s_waitcnt lgkmcnt(0)
	v_add_f32_e32 v5, v5, v6
	v_fmamk_f32 v5, v5, 0x3a800000, v184
	s_mov_b32 s9, 0x800000
	v_mul_f32_e32 v6, 0x4b800000, v5
	v_cmp_gt_f32_e32 vcc, s9, v5
	s_nop 1
	v_cndmask_b32_e32 v5, v5, v6, vcc
	v_rsq_f32_e32 v5, v5
	s_nop 0
	v_mul_f32_e32 v6, 0x45800000, v5
	v_cndmask_b32_e32 v5, v5, v6, vcc
	ds_write_b32 v3, v5 offset:1024
.LBB0_343:
	s_or_b64 exec, exec, s[12:13]
	v_readlane_b32 s12, v239, 46
	v_readlane_b32 s13, v239, 47
	s_andn2_b64 vcc, exec, s[12:13]
	s_cbranch_vccnz .LBB0_362
	v_readlane_b32 s9, v240, 58
	s_waitcnt lgkmcnt(0)
	s_nop 0
	v_add_u32_e32 v6, s9, v2
	v_ashrrev_i32_e32 v7, 31, v6
	v_lshlrev_b64 v[6:7], 6, v[6:7]
	v_lshl_add_u64 v[10:11], v[0:1], 0, v[6:7]
	s_nop 0
	s_waitcnt vmcnt(1)
	v_add_f32_e32 v5, v42, v43
	v_add_f32_e32 v5, v44, v5
	v_add_f32_e32 v5, v45, v5
	s_waitcnt vmcnt(0)
	v_add_f32_e32 v5, v46, v5
	v_add_f32_e32 v5, v47, v5
	v_add_f32_e32 v5, v48, v5
	v_add_f32_e32 v5, v49, v5
	ds_bpermute_b32 v6, v4, v5
	s_and_saveexec_b64 s[12:13], s[4:5]
	s_cbranch_execz .LBB0_346
	s_waitcnt lgkmcnt(0)
	v_add_f32_e32 v5, v5, v6
	v_fmamk_f32 v5, v5, 0x3a800000, v184
	s_mov_b32 s9, 0x800000
	v_mul_f32_e32 v6, 0x4b800000, v5
	v_cmp_gt_f32_e32 vcc, s9, v5
	s_nop 1
	v_cndmask_b32_e32 v5, v5, v6, vcc
	v_rsq_f32_e32 v5, v5
	s_nop 0
	v_mul_f32_e32 v6, 0x45800000, v5
	v_cndmask_b32_e32 v5, v5, v6, vcc
	ds_write_b32 v3, v5 offset:2048
.LBB0_346:
	s_or_b64 exec, exec, s[12:13]
	v_readlane_b32 s12, v239, 57
	v_readlane_b32 s13, v239, 58
	s_andn2_b64 vcc, exec, s[12:13]
	s_cbranch_vccnz .LBB0_362
	v_readlane_b32 s9, v240, 59
	s_waitcnt lgkmcnt(0)
	s_nop 0
	v_add_u32_e32 v6, s9, v2
	v_ashrrev_i32_e32 v7, 31, v6
	v_lshlrev_b64 v[6:7], 6, v[6:7]
	v_lshl_add_u64 v[10:11], v[0:1], 0, v[6:7]
	s_nop 0
	s_waitcnt vmcnt(1)
	v_add_f32_e32 v5, v50, v51
	v_add_f32_e32 v5, v52, v5
	v_add_f32_e32 v5, v53, v5
	s_waitcnt vmcnt(0)
	v_add_f32_e32 v5, v54, v5
	v_add_f32_e32 v5, v55, v5
	v_add_f32_e32 v5, v56, v5
	v_add_f32_e32 v5, v57, v5
	ds_bpermute_b32 v6, v4, v5
	s_and_saveexec_b64 s[12:13], s[4:5]
	s_cbranch_execz .LBB0_349
	s_waitcnt lgkmcnt(0)
	v_add_f32_e32 v5, v5, v6
	v_fmamk_f32 v5, v5, 0x3a800000, v184
	s_mov_b32 s9, 0x800000
	v_mul_f32_e32 v6, 0x4b800000, v5
	v_cmp_gt_f32_e32 vcc, s9, v5
	s_nop 1
	v_cndmask_b32_e32 v5, v5, v6, vcc
	v_rsq_f32_e32 v5, v5
	s_nop 0
	v_mul_f32_e32 v6, 0x45800000, v5
	v_cndmask_b32_e32 v5, v5, v6, vcc
	ds_write_b32 v3, v5 offset:3072
; DI void norm_prepass(const float* __restrict__ ss, const pg8::StaticOrder& S, LAS float* tab) {
;     ...
;   for (int i = 0; i < 8 && S.next(i, u); ++i) {
;     const f32x4* sp = (const f32x4*)(ss + (size_t)(u.pm * 256 + row) * 16 + half * 8);
;     const f32x4 a = sp[0], b = sp[1];
;     float t = a[0]; t += a[1]; t += a[2]; t += a[3]; t += b[0]; t += b[1]; t += b[2]; t += b[3];
;     const float o = shx(t, 1, tid & 63);
;     const float tot = half ? (o + t) : (t + o);
;     if (!half) tab[i * 256 + row] = rsqrtf(tot * (1.f / 1024.f) + EPS);
;   }
.LBB0_349:
	s_or_b64 exec, exec, s[12:13]
	v_readlane_b32 s12, v238, 3
	v_readlane_b32 s13, v238, 4
	s_andn2_b64 vcc, exec, s[12:13]
	s_cbranch_vccnz .LBB0_362
	v_readlane_b32 s9, v240, 60
	s_waitcnt lgkmcnt(0)
	s_nop 0
	v_add_u32_e32 v6, s9, v2
	v_ashrrev_i32_e32 v7, 31, v6
	v_lshlrev_b64 v[6:7], 6, v[6:7]
	v_lshl_add_u64 v[10:11], v[0:1], 0, v[6:7]
	s_nop 0
	s_waitcnt vmcnt(1)
	v_add_f32_e32 v5, v58, v59
	v_add_f32_e32 v5, v60, v5
	v_add_f32_e32 v5, v61, v5
	s_waitcnt vmcnt(0)
	v_add_f32_e32 v5, v62, v5
	v_add_f32_e32 v5, v63, v5
	v_add_f32_e32 v5, v64, v5
	v_add_f32_e32 v5, v65, v5
	ds_bpermute_b32 v6, v4, v5
	s_and_saveexec_b64 s[12:13], s[4:5]
	s_cbranch_execz .LBB0_352
	s_waitcnt lgkmcnt(0)
	v_add_f32_e32 v5, v5, v6
	v_fmamk_f32 v5, v5, 0x3a800000, v184
	s_mov_b32 s9, 0x800000
	v_mul_f32_e32 v6, 0x4b800000, v5
	v_cmp_gt_f32_e32 vcc, s9, v5
	s_nop 1
	v_cndmask_b32_e32 v5, v5, v6, vcc
	v_rsq_f32_e32 v5, v5
	s_nop 0
	v_mul_f32_e32 v6, 0x45800000, v5
	v_cndmask_b32_e32 v5, v5, v6, vcc
	ds_write_b32 v3, v5 offset:4096
.LBB0_352:
	s_or_b64 exec, exec, s[12:13]
	v_readlane_b32 s12, v238, 9
	v_readlane_b32 s13, v238, 10
	s_andn2_b64 vcc, exec, s[12:13]
	s_cbranch_vccnz .LBB0_362
	v_readlane_b32 s9, v240, 61
	s_waitcnt lgkmcnt(0)
	s_nop 0
	v_add_u32_e32 v6, s9, v2
	v_ashrrev_i32_e32 v7, 31, v6
	v_lshlrev_b64 v[6:7], 6, v[6:7]
	v_lshl_add_u64 v[10:11], v[0:1], 0, v[6:7]
	s_nop 0
	s_waitcnt vmcnt(1)
	v_add_f32_e32 v5, v66, v67
	v_add_f32_e32 v5, v68, v5
	v_add_f32_e32 v5, v69, v5
	s_waitcnt vmcnt(0)
	v_add_f32_e32 v5, v70, v5
	v_add_f32_e32 v5, v71, v5
	v_add_f32_e32 v5, v72, v5
	v_add_f32_e32 v5, v73, v5
	ds_bpermute_b32 v6, v4, v5
	s_and_saveexec_b64 s[12:13], s[4:5]
	s_cbranch_execz .LBB0_355
	s_waitcnt lgkmcnt(0)
	v_add_f32_e32 v5, v5, v6
	v_fmamk_f32 v5, v5, 0x3a800000, v184
	s_mov_b32 s9, 0x800000
	v_mul_f32_e32 v6, 0x4b800000, v5
	v_cmp_gt_f32_e32 vcc, s9, v5
	s_nop 1
	v_cndmask_b32_e32 v5, v5, v6, vcc
	v_rsq_f32_e32 v5, v5
	s_nop 0
	v_mul_f32_e32 v6, 0x45800000, v5
	v_cndmask_b32_e32 v5, v5, v6, vcc
	ds_write_b32 v3, v5 offset:5120
.LBB0_355:
	s_or_b64 exec, exec, s[12:13]
	v_readlane_b32 s12, v238, 15
	v_readlane_b32 s13, v238, 16
	s_andn2_b64 vcc, exec, s[12:13]
	s_cbranch_vccnz .LBB0_362
	v_readlane_b32 s9, v240, 62
	s_waitcnt lgkmcnt(0)
	s_nop 0
	v_add_u32_e32 v6, s9, v2
	v_ashrrev_i32_e32 v7, 31, v6
	v_lshlrev_b64 v[6:7], 6, v[6:7]
	v_lshl_add_u64 v[10:11], v[0:1], 0, v[6:7]
	s_nop 0
	s_waitcnt vmcnt(1)
	v_add_f32_e32 v5, v74, v75
	v_add_f32_e32 v5, v76, v5
	v_add_f32_e32 v5, v77, v5
	s_waitcnt vmcnt(0)
	v_add_f32_e32 v5, v78, v5
	v_add_f32_e32 v5, v79, v5
	v_add_f32_e32 v5, v80, v5
	v_add_f32_e32 v5, v81, v5
	ds_bpermute_b32 v6, v4, v5
	s_and_saveexec_b64 s[12:13], s[4:5]
	s_cbranch_execz .LBB0_358
	s_waitcnt lgkmcnt(0)
	v_add_f32_e32 v5, v5, v6
	v_fmamk_f32 v5, v5, 0x3a800000, v184
	s_mov_b32 s9, 0x800000
	v_mul_f32_e32 v6, 0x4b800000, v5
	v_cmp_gt_f32_e32 vcc, s9, v5
	s_nop 1
	v_cndmask_b32_e32 v5, v5, v6, vcc
	v_rsq_f32_e32 v5, v5
	s_nop 0
	v_mul_f32_e32 v6, 0x45800000, v5
	v_cndmask_b32_e32 v5, v5, v6, vcc
	ds_write_b32 v3, v5 offset:6144
.LBB0_358:
	s_or_b64 exec, exec, s[12:13]
	v_readlane_b32 s12, v238, 21
	v_readlane_b32 s13, v238, 22
	s_andn2_b64 vcc, exec, s[12:13]
	s_cbranch_vccnz .LBB0_362
	v_readlane_b32 s9, v240, 63
	s_waitcnt lgkmcnt(0)
	s_nop 0
	v_add_u32_e32 v6, s9, v2
	v_ashrrev_i32_e32 v7, 31, v6
	v_lshlrev_b64 v[6:7], 6, v[6:7]
	v_lshl_add_u64 v[0:1], v[0:1], 0, v[6:7]
	s_waitcnt vmcnt(1)
	v_add_f32_e32 v0, v82, v83
	v_add_f32_e32 v0, v84, v0
	v_add_f32_e32 v0, v85, v0
	s_waitcnt vmcnt(0)
	v_add_f32_e32 v0, v86, v0
	v_add_f32_e32 v0, v87, v0
	v_add_f32_e32 v0, v88, v0
	v_add_f32_e32 v0, v89, v0
	ds_bpermute_b32 v1, v4, v0
	s_and_saveexec_b64 s[12:13], s[4:5]
	s_cbranch_execz .LBB0_361
	s_waitcnt lgkmcnt(0)
	v_add_f32_e32 v0, v0, v1
	v_fmamk_f32 v0, v0, 0x3a800000, v184
	s_mov_b32 s4, 0x800000
	v_mul_f32_e32 v1, 0x4b800000, v0
	v_cmp_gt_f32_e32 vcc, s4, v0
	s_nop 1
	v_cndmask_b32_e32 v0, v0, v1, vcc
	v_rsq_f32_e32 v0, v0
	s_nop 0
	v_mul_f32_e32 v1, 0x45800000, v0
	v_cndmask_b32_e32 v0, v0, v1, vcc
	ds_write_b32 v3, v0 offset:7168

; DI int get_tid() { int t = threadIdx.x; asm volatile("" : "+v"(t)); return t; }
; #define LAS __attribute__((address_space(3)))
; DI void norm_prepass(const float* __restrict__ ss, const pg8::StaticOrder& S, LAS float* tab) {
;   const int tid = get_tid();
;   const int row = tid >> 1, half = tid & 1;
;   pg8::Unit u;
;   for (int i = 0; i < 8 && S.next(i, u); ++i) {
;     const f32x4* sp = (const f32x4*)(ss + (size_t)(u.pm * 256 + row) * 16 + half * 8);
;     const f32x4 a = sp[0], b = sp[1];
;     float t = a[0]; t += a[1]; t += a[2]; t += a[3]; t += b[0]; t += b[1]; t += b[2]; t += b[3];
;     const float o = shx(t, 1, tid & 63);
;     const float tot = half ? (o + t) : (t + o);
;     if (!half) tab[i * 256 + row] = rsqrtf(tot * (1.f / 1024.f) + EPS);
;   }
.LBB0_655:
	s_andn2_b64 vcc, exec, s[2:3]
	s_cbranch_vccnz .LBB0_1163
	s_mov_b64 s[2:3], 0
	v_readlane_b32 s4, v241, 1
	v_readlane_b32 s5, v241, 2
	s_add_u32 s10, s4, s2
	s_addc_u32 s11, s5, s3
	v_readlane_b32 s4, v240, 27
	v_readlane_b32 s5, v240, 28
	v_mov_b32_e32 v3, v182
	s_andn2_b64 vcc, exec, s[4:5]
	v_cndmask_b32_e64 v0, 0, 1, s[4:5]
	v_cmp_ne_u32_e64 s[2:3], 1, v0
	s_cbranch_vccnz .LBB0_681
	v_and_b32_e32 v14, 1, v3
	v_lshlrev_b32_e32 v144, 5, v14
	s_waitcnt lgkmcnt(0)
	v_lshl_add_u64 v[0:1], s[10:11], 0, v[144:145]
	s_mov_b64 s[4:5], 0x5fa4100
	v_ashrrev_i32_e32 v2, 1, v3
	v_lshl_add_u64 v[0:1], v[0:1], 0, s[4:5]
	v_readlane_b32 s4, v240, 29
	v_lshlrev_b32_e32 v3, 2, v3
	s_nop 0
	v_add_u32_e32 v4, s4, v2
	v_ashrrev_i32_e32 v5, 31, v4
	v_lshlrev_b64 v[4:5], 6, v[4:5]
	v_lshl_add_u64 v[4:5], v[0:1], 0, v[4:5]
	global_load_dwordx4 v[6:9], v[4:5], off
	global_load_dwordx4 v[10:13], v[4:5], off offset:16
	v_readlane_b32 s6, v238, 53
	v_readlane_b32 s7, v238, 54
	s_andn2_b64 vcc, exec, s[6:7]
	s_cbranch_vccnz .Lnpb_done
	v_readlane_b32 s6, v239, 0
	s_nop 0
	s_nop 0
	v_add_u32_e32 v90, s6, v2
	v_ashrrev_i32_e32 v91, 31, v90
	v_lshlrev_b64 v[90:91], 6, v[90:91]
	v_lshl_add_u64 v[92:93], v[0:1], 0, v[90:91]
	global_load_dwordx4 v[34:37], v[92:93], off
	s_nop 0
	global_load_dwordx4 v[38:41], v[92:93], off offset:16
	v_readlane_b32 s6, v239, 49
	v_readlane_b32 s7, v239, 50
	s_andn2_b64 vcc, exec, s[6:7]
	s_cbranch_vccnz .Lnpb_done
	v_readlane_b32 s6, v239, 1
	s_nop 0
	s_nop 0
	v_add_u32_e32 v90, s6, v2
	v_ashrrev_i32_e32 v91, 31, v90
	v_lshlrev_b64 v[90:91], 6, v[90:91]
	v_lshl_add_u64 v[92:93], v[0:1], 0, v[90:91]
	global_load_dwordx4 v[42:45], v[92:93], off
	s_nop 0
	global_load_dwordx4 v[46:49], v[92:93], off offset:16
	v_readlane_b32 s6, v239, 59
	v_readlane_b32 s7, v239, 60
	s_andn2_b64 vcc, exec, s[6:7]
	s_cbranch_vccnz .Lnpb_done
	v_readlane_b32 s6, v239, 2
	s_nop 0
	s_nop 0
	v_add_u32_e32 v90, s6, v2
	v_ashrrev_i32_e32 v91, 31, v90
	v_lshlrev_b64 v[90:91], 6, v[90:91]
	v_lshl_add_u64 v[92:93], v[0:1], 0, v[90:91]
	global_load_dwordx4 v[50:53], v[92:93], off
	s_nop 0
	global_load_dwordx4 v[54:57], v[92:93], off offset:16
	v_readlane_b32 s6, v238, 5
	v_readlane_b32 s7, v238, 6
	s_andn2_b64 vcc, exec, s[6:7]
	s_cbranch_vccnz .Lnpb_done
	v_readlane_b32 s6, v239, 3
	s_nop 0
	s_nop 0
	v_add_u32_e32 v90, s6, v2
	v_ashrrev_i32_e32 v91, 31, v90
	v_lshlrev_b64 v[90:91], 6, v[90:91]
	v_lshl_add_u64 v[92:93], v[0:1], 0, v[90:91]
	global_load_dwordx4 v[58:61], v[92:93], off
	s_nop 0
	global_load_dwordx4 v[62:65], v[92:93], off offset:16
	v_readlane_b32 s6, v238, 11
	v_readlane_b32 s7, v238, 12
	s_andn2_b64 vcc, exec, s[6:7]
	s_cbranch_vccnz .Lnpb_done
	v_readlane_b32 s6, v239, 4
	s_nop 0
	s_nop 0
	v_add_u32_e32 v90, s6, v2
	v_ashrrev_i32_e32 v91, 31, v90
	v_lshlrev_b64 v[90:91], 6, v[90:91]
	v_lshl_add_u64 v[92:93], v[0:1], 0, v[90:91]
	global_load_dwordx4 v[66:69], v[92:93], off
	s_nop 0
	global_load_dwordx4 v[70:73], v[92:93], off offset:16
	v_readlane_b32 s6, v238, 17
	v_readlane_b32 s7, v238, 18
	s_andn2_b64 vcc, exec, s[6:7]
	s_cbranch_vccnz .Lnpb_done
	v_readlane_b32 s6, v239, 5
	s_nop 0
	s_nop 0
	v_add_u32_e32 v90, s6, v2
	v_ashrrev_i32_e32 v91, 31, v90
	v_lshlrev_b64 v[90:91], 6, v[90:91]
	v_lshl_add_u64 v[92:93], v[0:1], 0, v[90:91]
	global_load_dwordx4 v[74:77], v[92:93], off
	s_nop 0
	global_load_dwordx4 v[78:81], v[92:93], off offset:16
	v_readlane_b32 s6, v238, 23
	v_readlane_b32 s7, v238, 24
	s_andn2_b64 vcc, exec, s[6:7]
	s_cbranch_vccnz .Lnpb_done
	v_readlane_b32 s6, v239, 6
	s_nop 0
	s_nop 0
	v_add_u32_e32 v90, s6, v2
	v_ashrrev_i32_e32 v91, 31, v90
	v_lshlrev_b64 v[90:91], 6, v[90:91]
	v_lshl_add_u64 v[92:93], v[0:1], 0, v[90:91]
	global_load_dwordx4 v[82:85], v[92:93], off
	global_load_dwordx4 v[86:89], v[92:93], off offset:16
.Lnpb_done:
	v_bitop3_b32 v4, v3, 4, v190 bitop3:0x6c
	v_readlane_b32 s4, v238, 44
	s_waitcnt vmcnt(0)
	v_add_f32_e32 v3, v6, v7
	v_add_f32_e32 v3, v8, v3
	v_add_f32_e32 v3, v9, v3
	v_add_f32_e32 v3, v10, v3
	v_add_f32_e32 v3, v11, v3
	v_add_f32_e32 v3, v12, v3
	v_add_f32_e32 v5, v13, v3
	ds_bpermute_b32 v6, v4, v5
	v_lshl_add_u32 v3, v2, 2, s4
	v_cmp_eq_u32_e64 s[4:5], 0, v14
	s_and_saveexec_b64 s[6:7], s[4:5]
	s_cbranch_execz .LBB0_659
	s_waitcnt lgkmcnt(0)
	v_add_f32_e32 v5, v5, v6
	v_fmamk_f32 v5, v5, 0x3a800000, v184
	s_mov_b32 s9, 0x800000
	v_mul_f32_e32 v6, 0x4b800000, v5
	v_cmp_gt_f32_e32 vcc, s9, v5
	s_nop 1
	v_cndmask_b32_e32 v5, v5, v6, vcc
	v_rsq_f32_e32 v5, v5
	s_nop 0
	v_mul_f32_e32 v6, 0x45800000, v5
	v_cndmask_b32_e32 v5, v5, v6, vcc
	ds_write_b32 v3, v5
.LBB0_659:
	s_or_b64 exec, exec, s[6:7]
	v_readlane_b32 s6, v238, 53
	v_readlane_b32 s7, v238, 54
	s_andn2_b64 vcc, exec, s[6:7]
	s_cbranch_vccnz .LBB0_681
	v_readlane_b32 s6, v239, 0
	s_waitcnt lgkmcnt(0)
	s_nop 0
	v_add_u32_e32 v6, s6, v2
	v_ashrrev_i32_e32 v7, 31, v6
	v_lshlrev_b64 v[6:7], 6, v[6:7]
	v_lshl_add_u64 v[10:11], v[0:1], 0, v[6:7]
	s_nop 0
	s_waitcnt vmcnt(1)
	v_add_f32_e32 v5, v34, v35
	v_add_f32_e32 v5, v36, v5
	v_add_f32_e32 v5, v37, v5
	s_waitcnt vmcnt(0)
	v_add_f32_e32 v5, v38, v5
	v_add_f32_e32 v5, v39, v5
	v_add_f32_e32 v5, v40, v5
	v_add_f32_e32 v5, v41, v5
	ds_bpermute_b32 v6, v4, v5
	s_and_saveexec_b64 s[6:7], s[4:5]
	s_cbranch_execz .LBB0_662
	s_waitcnt lgkmcnt(0)
	v_add_f32_e32 v5, v5, v6
	v_fmamk_f32 v5, v5, 0x3a800000, v184
	s_mov_b32 s9, 0x800000
	v_mul_f32_e32 v6, 0x4b800000, v5
	v_cmp_gt_f32_e32 vcc, s9, v5
	s_nop 1
	v_cndmask_b32_e32 v5, v5, v6, vcc
	v_rsq_f32_e32 v5, v5
	s_nop 0
	v_mul_f32_e32 v6, 0x45800000, v5
	v_cndmask_b32_e32 v5, v5, v6, vcc
	ds_write_b32 v3, v5 offset:1024
; DI void norm_prepass(const float* __restrict__ ss, const pg8::StaticOrder& S, LAS float* tab) {
;     ...
;   for (int i = 0; i < 8 && S.next(i, u); ++i) {
;     const f32x4* sp = (const f32x4*)(ss + (size_t)(u.pm * 256 + row) * 16 + half * 8);
;     const f32x4 a = sp[0], b = sp[1];
;     float t = a[0]; t += a[1]; t += a[2]; t += a[3]; t += b[0]; t += b[1]; t += b[2]; t += b[3];
;     const float o = shx(t, 1, tid & 63);
;     const float tot = half ? (o + t) : (t + o);
;     if (!half) tab[i * 256 + row] = rsqrtf(tot * (1.f / 1024.f) + EPS);
;   }
.LBB0_662:
	s_or_b64 exec, exec, s[6:7]
	v_readlane_b32 s6, v239, 49
	v_readlane_b32 s7, v239, 50
	s_andn2_b64 vcc, exec, s[6:7]
	s_cbranch_vccnz .LBB0_681
	v_readlane_b32 s6, v239, 1
	s_waitcnt lgkmcnt(0)
	s_nop 0
	v_add_u32_e32 v6, s6, v2
	v_ashrrev_i32_e32 v7, 31, v6
	v_lshlrev_b64 v[6:7], 6, v[6:7]
	v_lshl_add_u64 v[10:11], v[0:1], 0, v[6:7]
	s_nop 0
	s_waitcnt vmcnt(1)
	v_add_f32_e32 v5, v42, v43
	v_add_f32_e32 v5, v44, v5
	v_add_f32_e32 v5, v45, v5
	s_waitcnt vmcnt(0)
	v_add_f32_e32 v5, v46, v5
	v_add_f32_e32 v5, v47, v5
	v_add_f32_e32 v5, v48, v5
	v_add_f32_e32 v5, v49, v5
	ds_bpermute_b32 v6, v4, v5
	s_and_saveexec_b64 s[6:7], s[4:5]
	s_cbranch_execz .LBB0_665
	s_waitcnt lgkmcnt(0)
	v_add_f32_e32 v5, v5, v6
	v_fmamk_f32 v5, v5, 0x3a800000, v184
	s_mov_b32 s9, 0x800000
	v_mul_f32_e32 v6, 0x4b800000, v5
	v_cmp_gt_f32_e32 vcc, s9, v5
	s_nop 1
	v_cndmask_b32_e32 v5, v5, v6, vcc
	v_rsq_f32_e32 v5, v5
	s_nop 0
	v_mul_f32_e32 v6, 0x45800000, v5
	v_cndmask_b32_e32 v5, v5, v6, vcc
	ds_write_b32 v3, v5 offset:2048
.LBB0_665:
	s_or_b64 exec, exec, s[6:7]
	v_readlane_b32 s6, v239, 59
	v_readlane_b32 s7, v239, 60
	s_andn2_b64 vcc, exec, s[6:7]
	s_cbranch_vccnz .LBB0_681
	v_readlane_b32 s6, v239, 2
	s_waitcnt lgkmcnt(0)
	s_nop 0
	v_add_u32_e32 v6, s6, v2
	v_ashrrev_i32_e32 v7, 31, v6
	v_lshlrev_b64 v[6:7], 6, v[6:7]
	v_lshl_add_u64 v[10:11], v[0:1], 0, v[6:7]
	s_nop 0
	s_waitcnt vmcnt(1)
	v_add_f32_e32 v5, v50, v51
	v_add_f32_e32 v5, v52, v5
	v_add_f32_e32 v5, v53, v5
	s_waitcnt vmcnt(0)
	v_add_f32_e32 v5, v54, v5
	v_add_f32_e32 v5, v55, v5
	v_add_f32_e32 v5, v56, v5
	v_add_f32_e32 v5, v57, v5
	ds_bpermute_b32 v6, v4, v5
	s_and_saveexec_b64 s[6:7], s[4:5]
	s_cbranch_execz .LBB0_668
	s_waitcnt lgkmcnt(0)
	v_add_f32_e32 v5, v5, v6
	v_fmamk_f32 v5, v5, 0x3a800000, v184
	s_mov_b32 s9, 0x800000
	v_mul_f32_e32 v6, 0x4b800000, v5
	v_cmp_gt_f32_e32 vcc, s9, v5
	s_nop 1
	v_cndmask_b32_e32 v5, v5, v6, vcc
	v_rsq_f32_e32 v5, v5
	s_nop 0
	v_mul_f32_e32 v6, 0x45800000, v5
	v_cndmask_b32_e32 v5, v5, v6, vcc
	ds_write_b32 v3, v5 offset:3072
.LBB0_668:
	s_or_b64 exec, exec, s[6:7]
	v_readlane_b32 s6, v238, 5
	v_readlane_b32 s7, v238, 6
	s_andn2_b64 vcc, exec, s[6:7]
	s_cbranch_vccnz .LBB0_681
	v_readlane_b32 s6, v239, 3
	s_waitcnt lgkmcnt(0)
	s_nop 0
	v_add_u32_e32 v6, s6, v2
	v_ashrrev_i32_e32 v7, 31, v6
	v_lshlrev_b64 v[6:7], 6, v[6:7]
	v_lshl_add_u64 v[10:11], v[0:1], 0, v[6:7]
	s_nop 0
	s_waitcnt vmcnt(1)
	v_add_f32_e32 v5, v58, v59
	v_add_f32_e32 v5, v60, v5
	v_add_f32_e32 v5, v61, v5
	s_waitcnt vmcnt(0)
	v_add_f32_e32 v5, v62, v5
	v_add_f32_e32 v5, v63, v5
	v_add_f32_e32 v5, v64, v5
	v_add_f32_e32 v5, v65, v5
	ds_bpermute_b32 v6, v4, v5
	s_and_saveexec_b64 s[6:7], s[4:5]
	s_cbranch_execz .LBB0_671
	s_waitcnt lgkmcnt(0)
	v_add_f32_e32 v5, v5, v6
	v_fmamk_f32 v5, v5, 0x3a800000, v184
	s_mov_b32 s9, 0x800000
	v_mul_f32_e32 v6, 0x4b800000, v5
	v_cmp_gt_f32_e32 vcc, s9, v5
	s_nop 1
	v_cndmask_b32_e32 v5, v5, v6, vcc
	v_rsq_f32_e32 v5, v5
	s_nop 0
	v_mul_f32_e32 v6, 0x45800000, v5
	v_cndmask_b32_e32 v5, v5, v6, vcc
	ds_write_b32 v3, v5 offset:4096
.LBB0_671:
	s_or_b64 exec, exec, s[6:7]
	v_readlane_b32 s6, v238, 11
	v_readlane_b32 s7, v238, 12
	s_andn2_b64 vcc, exec, s[6:7]
	s_cbranch_vccnz .LBB0_681
	v_readlane_b32 s6, v239, 4
	s_waitcnt lgkmcnt(0)
	s_nop 0
	v_add_u32_e32 v6, s6, v2
	v_ashrrev_i32_e32 v7, 31, v6
	v_lshlrev_b64 v[6:7], 6, v[6:7]
	v_lshl_add_u64 v[10:11], v[0:1], 0, v[6:7]
	s_nop 0
	s_waitcnt vmcnt(1)
	v_add_f32_e32 v5, v66, v67
	v_add_f32_e32 v5, v68, v5
	v_add_f32_e32 v5, v69, v5
	s_waitcnt vmcnt(0)
	v_add_f32_e32 v5, v70, v5
	v_add_f32_e32 v5, v71, v5
	v_add_f32_e32 v5, v72, v5
	v_add_f32_e32 v5, v73, v5
	ds_bpermute_b32 v6, v4, v5
	s_and_saveexec_b64 s[6:7], s[4:5]
	s_cbranch_execz .LBB0_674
	s_waitcnt lgkmcnt(0)
	v_add_f32_e32 v5, v5, v6
	v_fmamk_f32 v5, v5, 0x3a800000, v184
	s_mov_b32 s9, 0x800000
	v_mul_f32_e32 v6, 0x4b800000, v5
	v_cmp_gt_f32_e32 vcc, s9, v5
	s_nop 1
	v_cndmask_b32_e32 v5, v5, v6, vcc
	v_rsq_f32_e32 v5, v5
	s_nop 0
	v_mul_f32_e32 v6, 0x45800000, v5
	v_cndmask_b32_e32 v5, v5, v6, vcc
	ds_write_b32 v3, v5 offset:5120
.LBB0_674:
	s_or_b64 exec, exec, s[6:7]
	v_readlane_b32 s6, v238, 17
	v_readlane_b32 s7, v238, 18
	s_andn2_b64 vcc, exec, s[6:7]
	s_cbranch_vccnz .LBB0_681
	v_readlane_b32 s6, v239, 5
	s_waitcnt lgkmcnt(0)
	s_nop 0
	v_add_u32_e32 v6, s6, v2
	v_ashrrev_i32_e32 v7, 31, v6
	v_lshlrev_b64 v[6:7], 6, v[6:7]
	v_lshl_add_u64 v[10:11], v[0:1], 0, v[6:7]
	s_nop 0
	s_waitcnt vmcnt(1)
	v_add_f32_e32 v5, v74, v75
	v_add_f32_e32 v5, v76, v5
	v_add_f32_e32 v5, v77, v5
	s_waitcnt vmcnt(0)
	v_add_f32_e32 v5, v78, v5
	v_add_f32_e32 v5, v79, v5
	v_add_f32_e32 v5, v80, v5
	v_add_f32_e32 v5, v81, v5
	ds_bpermute_b32 v6, v4, v5
	s_and_saveexec_b64 s[6:7], s[4:5]
	s_cbranch_execz .LBB0_677
	s_waitcnt lgkmcnt(0)
	v_add_f32_e32 v5, v5, v6
	v_fmamk_f32 v5, v5, 0x3a800000, v184
	s_mov_b32 s9, 0x800000
	v_mul_f32_e32 v6, 0x4b800000, v5
	v_cmp_gt_f32_e32 vcc, s9, v5
	s_nop 1
	v_cndmask_b32_e32 v5, v5, v6, vcc
	v_rsq_f32_e32 v5, v5
	s_nop 0
	v_mul_f32_e32 v6, 0x45800000, v5
	v_cndmask_b32_e32 v5, v5, v6, vcc
	ds_write_b32 v3, v5 offset:6144
.LBB0_677:
	s_or_b64 exec, exec, s[6:7]
	v_readlane_b32 s6, v238, 23
	v_readlane_b32 s7, v238, 24
	s_andn2_b64 vcc, exec, s[6:7]
	s_cbranch_vccnz .LBB0_681
	v_readlane_b32 s6, v239, 6
	s_waitcnt lgkmcnt(0)
	s_nop 0
	v_add_u32_e32 v6, s6, v2
	v_ashrrev_i32_e32 v7, 31, v6
	v_lshlrev_b64 v[6:7], 6, v[6:7]
	v_lshl_add_u64 v[0:1], v[0:1], 0, v[6:7]
	s_waitcnt vmcnt(1)
	v_add_f32_e32 v0, v82, v83
	v_add_f32_e32 v0, v84, v0
	v_add_f32_e32 v0, v85, v0
	s_waitcnt vmcnt(0)
	v_add_f32_e32 v0, v86, v0
	v_add_f32_e32 v0, v87, v0
	v_add_f32_e32 v0, v88, v0
	v_add_f32_e32 v0, v89, v0
	ds_bpermute_b32 v1, v4, v0
	s_and_saveexec_b64 s[6:7], s[4:5]
	s_cbranch_execz .LBB0_680
	s_waitcnt lgkmcnt(0)
	v_add_f32_e32 v0, v0, v1
	v_fmamk_f32 v0, v0, 0x3a800000, v184
	s_mov_b32 s4, 0x800000
	v_mul_f32_e32 v1, 0x4b800000, v0
	v_cmp_gt_f32_e32 vcc, s4, v0
	s_nop 1
	v_cndmask_b32_e32 v0, v0, v1, vcc
	v_rsq_f32_e32 v0, v0
	s_nop 0
	v_mul_f32_e32 v1, 0x45800000, v0
	v_cndmask_b32_e32 v0, v0, v1, vcc
	ds_write_b32 v3, v0 offset:7168

; DI int get_tid() { int t = threadIdx.x; asm volatile("" : "+v"(t)); return t; }
; #define LAS __attribute__((address_space(3)))
; DI void norm_prepass(const float* __restrict__ ss, const pg8::StaticOrder& S, LAS float* tab) {
;   const int tid = get_tid();
;   const int row = tid >> 1, half = tid & 1;
;   pg8::Unit u;
;   for (int i = 0; i < 8 && S.next(i, u); ++i) {
;     const f32x4* sp = (const f32x4*)(ss + (size_t)(u.pm * 256 + row) * 16 + half * 8);
;     const f32x4 a = sp[0], b = sp[1];
;     float t = a[0]; t += a[1]; t += a[2]; t += a[3]; t += b[0]; t += b[1]; t += b[2]; t += b[3];
;     const float o = shx(t, 1, tid & 63);
;     const float tot = half ? (o + t) : (t + o);
;     if (!half) tab[i * 256 + row] = rsqrtf(tot * (1.f / 1024.f) + EPS);
;   }
.LBB0_1792:
	s_andn2_b64 vcc, exec, s[2:3]
	s_cbranch_vccnz .LBB0_1888
	s_mov_b64 s[2:3], 0
	v_readlane_b32 s4, v241, 1
	v_readlane_b32 s5, v241, 2
	s_add_u32 s6, s4, s2
	s_addc_u32 s7, s5, s3
	v_readlane_b32 s4, v240, 40
	v_readlane_b32 s5, v240, 41
	v_mov_b32_e32 v3, v182
	s_andn2_b64 vcc, exec, s[4:5]
	v_cndmask_b32_e64 v0, 0, 1, s[4:5]
	v_cmp_ne_u32_e64 s[2:3], 1, v0
	s_cbranch_vccnz .LBB0_1818
	v_and_b32_e32 v14, 1, v3
	v_lshlrev_b32_e32 v144, 5, v14
	s_waitcnt lgkmcnt(0)
	v_lshl_add_u64 v[0:1], s[6:7], 0, v[144:145]
	s_mov_b64 s[4:5], 0x61a4100
	v_ashrrev_i32_e32 v2, 1, v3
	v_lshl_add_u64 v[0:1], v[0:1], 0, s[4:5]
	v_readlane_b32 s4, v240, 42
	v_lshlrev_b32_e32 v3, 2, v3
	s_nop 0
	v_add_u32_e32 v4, s4, v2
	v_ashrrev_i32_e32 v5, 31, v4
	v_lshlrev_b64 v[4:5], 6, v[4:5]
	v_lshl_add_u64 v[4:5], v[0:1], 0, v[4:5]
	global_load_dwordx4 v[6:9], v[4:5], off
	global_load_dwordx4 v[10:13], v[4:5], off offset:16
	v_readlane_b32 s10, v238, 63
	v_readlane_b32 s11, v237, 0
	s_andn2_b64 vcc, exec, s[10:11]
	s_cbranch_vccnz .Lnpc_done
	v_readlane_b32 s9, v239, 31
	s_nop 0
	s_nop 0
	v_add_u32_e32 v90, s9, v2
	v_ashrrev_i32_e32 v91, 31, v90
	v_lshlrev_b64 v[90:91], 6, v[90:91]
	v_lshl_add_u64 v[92:93], v[0:1], 0, v[90:91]
	global_load_dwordx4 v[34:37], v[92:93], off
	s_nop 0
	global_load_dwordx4 v[38:41], v[92:93], off offset:16
	v_readlane_b32 s10, v239, 55
	v_readlane_b32 s11, v239, 56
	s_andn2_b64 vcc, exec, s[10:11]
	s_cbranch_vccnz .Lnpc_done
	v_readlane_b32 s9, v239, 32
	s_nop 0
	s_nop 0
	v_add_u32_e32 v90, s9, v2
	v_ashrrev_i32_e32 v91, 31, v90
	v_lshlrev_b64 v[90:91], 6, v[90:91]
	v_lshl_add_u64 v[92:93], v[0:1], 0, v[90:91]
	global_load_dwordx4 v[42:45], v[92:93], off
	s_nop 0
	global_load_dwordx4 v[46:49], v[92:93], off offset:16
	v_readlane_b32 s10, v238, 1
	v_readlane_b32 s11, v238, 2
	s_andn2_b64 vcc, exec, s[10:11]
	s_cbranch_vccnz .Lnpc_done
	v_readlane_b32 s9, v239, 33
	s_nop 0
	s_nop 0
	v_add_u32_e32 v90, s9, v2
	v_ashrrev_i32_e32 v91, 31, v90
	v_lshlrev_b64 v[90:91], 6, v[90:91]
	v_lshl_add_u64 v[92:93], v[0:1], 0, v[90:91]
	global_load_dwordx4 v[50:53], v[92:93], off
	s_nop 0
	global_load_dwordx4 v[54:57], v[92:93], off offset:16
	v_readlane_b32 s10, v238, 7
	v_readlane_b32 s11, v238, 8
	s_andn2_b64 vcc, exec, s[10:11]
	s_cbranch_vccnz .Lnpc_done
	v_readlane_b32 s9, v239, 34
	s_nop 0
	s_nop 0
	v_add_u32_e32 v90, s9, v2
	v_ashrrev_i32_e32 v91, 31, v90
	v_lshlrev_b64 v[90:91], 6, v[90:91]
	v_lshl_add_u64 v[92:93], v[0:1], 0, v[90:91]
	global_load_dwordx4 v[58:61], v[92:93], off
	s_nop 0
	global_load_dwordx4 v[62:65], v[92:93], off offset:16
	v_readlane_b32 s10, v238, 13
	v_readlane_b32 s11, v238, 14
	s_andn2_b64 vcc, exec, s[10:11]
	s_cbranch_vccnz .Lnpc_done
	v_readlane_b32 s9, v239, 35
	s_nop 0
	s_nop 0
	v_add_u32_e32 v90, s9, v2
	v_ashrrev_i32_e32 v91, 31, v90
	v_lshlrev_b64 v[90:91], 6, v[90:91]
	v_lshl_add_u64 v[92:93], v[0:1], 0, v[90:91]
	global_load_dwordx4 v[66:69], v[92:93], off
	s_nop 0
	global_load_dwordx4 v[70:73], v[92:93], off offset:16
	v_readlane_b32 s10, v238, 19
	v_readlane_b32 s11, v238, 20
	s_andn2_b64 vcc, exec, s[10:11]
	s_cbranch_vccnz .Lnpc_done
	v_readlane_b32 s9, v239, 36
	s_nop 0
	s_nop 0
	v_add_u32_e32 v90, s9, v2
	v_ashrrev_i32_e32 v91, 31, v90
	v_lshlrev_b64 v[90:91], 6, v[90:91]
	v_lshl_add_u64 v[92:93], v[0:1], 0, v[90:91]
	global_load_dwordx4 v[74:77], v[92:93], off
	s_nop 0
	global_load_dwordx4 v[78:81], v[92:93], off offset:16
	v_readlane_b32 s10, v238, 25
	v_readlane_b32 s11, v238, 26
	s_andn2_b64 vcc, exec, s[10:11]
	s_cbranch_vccnz .Lnpc_done
	v_readlane_b32 s9, v239, 37
	s_nop 0
	s_nop 0
	v_add_u32_e32 v90, s9, v2
	v_ashrrev_i32_e32 v91, 31, v90
	v_lshlrev_b64 v[90:91], 6, v[90:91]
	v_lshl_add_u64 v[92:93], v[0:1], 0, v[90:91]
	global_load_dwordx4 v[82:85], v[92:93], off
	global_load_dwordx4 v[86:89], v[92:93], off offset:16
.Lnpc_done:
	v_bitop3_b32 v4, v3, 4, v190 bitop3:0x6c
	v_readlane_b32 s4, v238, 44
	s_waitcnt vmcnt(0)
	v_add_f32_e32 v3, v6, v7
	v_add_f32_e32 v3, v8, v3
	v_add_f32_e32 v3, v9, v3
	v_add_f32_e32 v3, v10, v3
	v_add_f32_e32 v3, v11, v3
	v_add_f32_e32 v3, v12, v3
	v_add_f32_e32 v5, v13, v3
	ds_bpermute_b32 v6, v4, v5
	v_lshl_add_u32 v3, v2, 2, s4
	v_cmp_eq_u32_e64 s[4:5], 0, v14
	s_and_saveexec_b64 s[10:11], s[4:5]
	s_cbranch_execz .LBB0_1796
	s_waitcnt lgkmcnt(0)
	v_add_f32_e32 v5, v5, v6
	v_fmamk_f32 v5, v5, 0x3a800000, v184
	s_mov_b32 s9, 0x800000
	v_mul_f32_e32 v6, 0x4b800000, v5
	v_cmp_gt_f32_e32 vcc, s9, v5
	s_nop 1
	v_cndmask_b32_e32 v5, v5, v6, vcc
	v_rsq_f32_e32 v5, v5
	s_nop 0
	v_mul_f32_e32 v6, 0x45800000, v5
	v_cndmask_b32_e32 v5, v5, v6, vcc
	ds_write_b32 v3, v5
.LBB0_1796:
	s_or_b64 exec, exec, s[10:11]
	v_readlane_b32 s10, v238, 63
	v_readlane_b32 s11, v237, 0
	s_andn2_b64 vcc, exec, s[10:11]
	s_cbranch_vccnz .LBB0_1818
	v_readlane_b32 s9, v239, 31
	s_waitcnt lgkmcnt(0)
	s_nop 0
	v_add_u32_e32 v6, s9, v2
	v_ashrrev_i32_e32 v7, 31, v6
	v_lshlrev_b64 v[6:7], 6, v[6:7]
	v_lshl_add_u64 v[10:11], v[0:1], 0, v[6:7]
	s_nop 0
	s_waitcnt vmcnt(1)
	v_add_f32_e32 v5, v34, v35
	v_add_f32_e32 v5, v36, v5
	v_add_f32_e32 v5, v37, v5
	s_waitcnt vmcnt(0)
	v_add_f32_e32 v5, v38, v5
	v_add_f32_e32 v5, v39, v5
	v_add_f32_e32 v5, v40, v5
	v_add_f32_e32 v5, v41, v5
	ds_bpermute_b32 v6, v4, v5
	s_and_saveexec_b64 s[10:11], s[4:5]
	s_cbranch_execz .LBB0_1799
	s_waitcnt lgkmcnt(0)
	v_add_f32_e32 v5, v5, v6
	v_fmamk_f32 v5, v5, 0x3a800000, v184
	s_mov_b32 s9, 0x800000
	v_mul_f32_e32 v6, 0x4b800000, v5
	v_cmp_gt_f32_e32 vcc, s9, v5
	s_nop 1
	v_cndmask_b32_e32 v5, v5, v6, vcc
	v_rsq_f32_e32 v5, v5
	s_nop 0
	v_mul_f32_e32 v6, 0x45800000, v5
	v_cndmask_b32_e32 v5, v5, v6, vcc
	ds_write_b32 v3, v5 offset:1024
; DI void norm_prepass(const float* __restrict__ ss, const pg8::StaticOrder& S, LAS float* tab) {
;     ...
;   for (int i = 0; i < 8 && S.next(i, u); ++i) {
;     const f32x4* sp = (const f32x4*)(ss + (size_t)(u.pm * 256 + row) * 16 + half * 8);
;     const f32x4 a = sp[0], b = sp[1];
;     float t = a[0]; t += a[1]; t += a[2]; t += a[3]; t += b[0]; t += b[1]; t += b[2]; t += b[3];
;     const float o = shx(t, 1, tid & 63);
;     const float tot = half ? (o + t) : (t + o);
;     if (!half) tab[i * 256 + row] = rsqrtf(tot * (1.f / 1024.f) + EPS);
;   }
.LBB0_1799:
	s_or_b64 exec, exec, s[10:11]
	v_readlane_b32 s10, v239, 55
	v_readlane_b32 s11, v239, 56
	s_andn2_b64 vcc, exec, s[10:11]
	s_cbranch_vccnz .LBB0_1818
	v_readlane_b32 s9, v239, 32
	s_waitcnt lgkmcnt(0)
	s_nop 0
	v_add_u32_e32 v6, s9, v2
	v_ashrrev_i32_e32 v7, 31, v6
	v_lshlrev_b64 v[6:7], 6, v[6:7]
	v_lshl_add_u64 v[10:11], v[0:1], 0, v[6:7]
	s_nop 0
	s_waitcnt vmcnt(1)
	v_add_f32_e32 v5, v42, v43
	v_add_f32_e32 v5, v44, v5
	v_add_f32_e32 v5, v45, v5
	s_waitcnt vmcnt(0)
	v_add_f32_e32 v5, v46, v5
	v_add_f32_e32 v5, v47, v5
	v_add_f32_e32 v5, v48, v5
	v_add_f32_e32 v5, v49, v5
	ds_bpermute_b32 v6, v4, v5
	s_and_saveexec_b64 s[10:11], s[4:5]
	s_cbranch_execz .LBB0_1802
	s_waitcnt lgkmcnt(0)
	v_add_f32_e32 v5, v5, v6
	v_fmamk_f32 v5, v5, 0x3a800000, v184
	s_mov_b32 s9, 0x800000
	v_mul_f32_e32 v6, 0x4b800000, v5
	v_cmp_gt_f32_e32 vcc, s9, v5
	s_nop 1
	v_cndmask_b32_e32 v5, v5, v6, vcc
	v_rsq_f32_e32 v5, v5
	s_nop 0
	v_mul_f32_e32 v6, 0x45800000, v5
	v_cndmask_b32_e32 v5, v5, v6, vcc
	ds_write_b32 v3, v5 offset:2048
.LBB0_1802:
	s_or_b64 exec, exec, s[10:11]
	v_readlane_b32 s10, v238, 1
	v_readlane_b32 s11, v238, 2
	s_andn2_b64 vcc, exec, s[10:11]
	s_cbranch_vccnz .LBB0_1818
	v_readlane_b32 s9, v239, 33
	s_waitcnt lgkmcnt(0)
	s_nop 0
	v_add_u32_e32 v6, s9, v2
	v_ashrrev_i32_e32 v7, 31, v6
	v_lshlrev_b64 v[6:7], 6, v[6:7]
	v_lshl_add_u64 v[10:11], v[0:1], 0, v[6:7]
	s_nop 0
	s_waitcnt vmcnt(1)
	v_add_f32_e32 v5, v50, v51
	v_add_f32_e32 v5, v52, v5
	v_add_f32_e32 v5, v53, v5
	s_waitcnt vmcnt(0)
	v_add_f32_e32 v5, v54, v5
	v_add_f32_e32 v5, v55, v5
	v_add_f32_e32 v5, v56, v5
	v_add_f32_e32 v5, v57, v5
	ds_bpermute_b32 v6, v4, v5
	s_and_saveexec_b64 s[10:11], s[4:5]
	s_cbranch_execz .LBB0_1805
	s_waitcnt lgkmcnt(0)
	v_add_f32_e32 v5, v5, v6
	v_fmamk_f32 v5, v5, 0x3a800000, v184
	s_mov_b32 s9, 0x800000
	v_mul_f32_e32 v6, 0x4b800000, v5
	v_cmp_gt_f32_e32 vcc, s9, v5
	s_nop 1
	v_cndmask_b32_e32 v5, v5, v6, vcc
	v_rsq_f32_e32 v5, v5
	s_nop 0
	v_mul_f32_e32 v6, 0x45800000, v5
	v_cndmask_b32_e32 v5, v5, v6, vcc
	ds_write_b32 v3, v5 offset:3072
.LBB0_1805:
	s_or_b64 exec, exec, s[10:11]
	v_readlane_b32 s10, v238, 7
	v_readlane_b32 s11, v238, 8
	s_andn2_b64 vcc, exec, s[10:11]
	s_cbranch_vccnz .LBB0_1818
	v_readlane_b32 s9, v239, 34
	s_waitcnt lgkmcnt(0)
	s_nop 0
	v_add_u32_e32 v6, s9, v2
	v_ashrrev_i32_e32 v7, 31, v6
	v_lshlrev_b64 v[6:7], 6, v[6:7]
	v_lshl_add_u64 v[10:11], v[0:1], 0, v[6:7]
	s_nop 0
	s_waitcnt vmcnt(1)
	v_add_f32_e32 v5, v58, v59
	v_add_f32_e32 v5, v60, v5
	v_add_f32_e32 v5, v61, v5
	s_waitcnt vmcnt(0)
	v_add_f32_e32 v5, v62, v5
	v_add_f32_e32 v5, v63, v5
	v_add_f32_e32 v5, v64, v5
	v_add_f32_e32 v5, v65, v5
	ds_bpermute_b32 v6, v4, v5
	s_and_saveexec_b64 s[10:11], s[4:5]
	s_cbranch_execz .LBB0_1808
	s_waitcnt lgkmcnt(0)
	v_add_f32_e32 v5, v5, v6
	v_fmamk_f32 v5, v5, 0x3a800000, v184
	s_mov_b32 s9, 0x800000
	v_mul_f32_e32 v6, 0x4b800000, v5
	v_cmp_gt_f32_e32 vcc, s9, v5
	s_nop 1
	v_cndmask_b32_e32 v5, v5, v6, vcc
	v_rsq_f32_e32 v5, v5
	s_nop 0
	v_mul_f32_e32 v6, 0x45800000, v5
	v_cndmask_b32_e32 v5, v5, v6, vcc
	ds_write_b32 v3, v5 offset:4096
.LBB0_1808:
	s_or_b64 exec, exec, s[10:11]
	v_readlane_b32 s10, v238, 13
	v_readlane_b32 s11, v238, 14
	s_andn2_b64 vcc, exec, s[10:11]
	s_cbranch_vccnz .LBB0_1818
	v_readlane_b32 s9, v239, 35
	s_waitcnt lgkmcnt(0)
	s_nop 0
	v_add_u32_e32 v6, s9, v2
	v_ashrrev_i32_e32 v7, 31, v6
	v_lshlrev_b64 v[6:7], 6, v[6:7]
	v_lshl_add_u64 v[10:11], v[0:1], 0, v[6:7]
	s_nop 0
	s_waitcnt vmcnt(1)
	v_add_f32_e32 v5, v66, v67
	v_add_f32_e32 v5, v68, v5
	v_add_f32_e32 v5, v69, v5
	s_waitcnt vmcnt(0)
	v_add_f32_e32 v5, v70, v5
	v_add_f32_e32 v5, v71, v5
	v_add_f32_e32 v5, v72, v5
	v_add_f32_e32 v5, v73, v5
	ds_bpermute_b32 v6, v4, v5
	s_and_saveexec_b64 s[10:11], s[4:5]
	s_cbranch_execz .LBB0_1811
	s_waitcnt lgkmcnt(0)
	v_add_f32_e32 v5, v5, v6
	v_fmamk_f32 v5, v5, 0x3a800000, v184
	s_mov_b32 s9, 0x800000
	v_mul_f32_e32 v6, 0x4b800000, v5
	v_cmp_gt_f32_e32 vcc, s9, v5
	s_nop 1
	v_cndmask_b32_e32 v5, v5, v6, vcc
	v_rsq_f32_e32 v5, v5
	s_nop 0
	v_mul_f32_e32 v6, 0x45800000, v5
	v_cndmask_b32_e32 v5, v5, v6, vcc
	ds_write_b32 v3, v5 offset:5120
.LBB0_1811:
	s_or_b64 exec, exec, s[10:11]
	v_readlane_b32 s10, v238, 19
	v_readlane_b32 s11, v238, 20
	s_andn2_b64 vcc, exec, s[10:11]
	s_cbranch_vccnz .LBB0_1818
	v_readlane_b32 s9, v239, 36
	s_waitcnt lgkmcnt(0)
	s_nop 0
	v_add_u32_e32 v6, s9, v2
	v_ashrrev_i32_e32 v7, 31, v6
	v_lshlrev_b64 v[6:7], 6, v[6:7]
	v_lshl_add_u64 v[10:11], v[0:1], 0, v[6:7]
	s_nop 0
	s_waitcnt vmcnt(1)
	v_add_f32_e32 v5, v74, v75
	v_add_f32_e32 v5, v76, v5
	v_add_f32_e32 v5, v77, v5
	s_waitcnt vmcnt(0)
	v_add_f32_e32 v5, v78, v5
	v_add_f32_e32 v5, v79, v5
	v_add_f32_e32 v5, v80, v5
	v_add_f32_e32 v5, v81, v5
	ds_bpermute_b32 v6, v4, v5
	s_and_saveexec_b64 s[10:11], s[4:5]
	s_cbranch_execz .LBB0_1814
	s_waitcnt lgkmcnt(0)
	v_add_f32_e32 v5, v5, v6
	v_fmamk_f32 v5, v5, 0x3a800000, v184
	s_mov_b32 s9, 0x800000
	v_mul_f32_e32 v6, 0x4b800000, v5
	v_cmp_gt_f32_e32 vcc, s9, v5
	s_nop 1
	v_cndmask_b32_e32 v5, v5, v6, vcc
	v_rsq_f32_e32 v5, v5
	s_nop 0
	v_mul_f32_e32 v6, 0x45800000, v5
	v_cndmask_b32_e32 v5, v5, v6, vcc
	ds_write_b32 v3, v5 offset:6144
.LBB0_1814:
	s_or_b64 exec, exec, s[10:11]
	v_readlane_b32 s10, v238, 25
	v_readlane_b32 s11, v238, 26
	s_andn2_b64 vcc, exec, s[10:11]
	s_cbranch_vccnz .LBB0_1818
	v_readlane_b32 s9, v239, 37
	s_waitcnt lgkmcnt(0)
	s_nop 0
	v_add_u32_e32 v6, s9, v2
	v_ashrrev_i32_e32 v7, 31, v6
	v_lshlrev_b64 v[6:7], 6, v[6:7]
	v_lshl_add_u64 v[0:1], v[0:1], 0, v[6:7]
	s_waitcnt vmcnt(1)
	v_add_f32_e32 v0, v82, v83
	v_add_f32_e32 v0, v84, v0
	v_add_f32_e32 v0, v85, v0
	s_waitcnt vmcnt(0)
	v_add_f32_e32 v0, v86, v0
	v_add_f32_e32 v0, v87, v0
	v_add_f32_e32 v0, v88, v0
	v_add_f32_e32 v0, v89, v0
	ds_bpermute_b32 v1, v4, v0
	s_and_saveexec_b64 s[10:11], s[4:5]
	s_cbranch_execz .LBB0_1817
	s_waitcnt lgkmcnt(0)
	v_add_f32_e32 v0, v0, v1
	v_fmamk_f32 v0, v0, 0x3a800000, v184
	s_mov_b32 s4, 0x800000
	v_mul_f32_e32 v1, 0x4b800000, v0
	v_cmp_gt_f32_e32 vcc, s4, v0
	s_nop 1
	v_cndmask_b32_e32 v0, v0, v1, vcc
	v_rsq_f32_e32 v0, v0
	s_nop 0
	v_mul_f32_e32 v1, 0x45800000, v0
	v_cndmask_b32_e32 v0, v0, v1, vcc
	ds_write_b32 v3, v0 offset:7168
